# v36 + s_setprio 1/0 around the QK and PV MFMA clusters of the attention kv loop
# speedup vs baseline: 1.0055x; 1.0055x over previous
; #define MFMA(a, b, c) __builtin_amdgcn_mfma_f32_32x32x16_bf16((a), (b), (c), 0, 0, 0)
; DI void phase4(const Params& p, char* smem) {
;     ...
;         f32x16 s;
; #pragma unroll
;         for (int i = 0; i < 16; ++i) s[i] = 0.f;
;         const u16* kp = Ks + (kh * 32 + r) * 200 + hi * 8;
;         {
;           bf16x8 kf[4];
; #pragma unroll
;           for (int i = 0; i < 4; ++i) kf[i] = *(const bf16x8*)(kp + i * 16);
; #pragma unroll
;           for (int ks = 0; ks < 12; ++ks) {
;             __builtin_amdgcn_sched_barrier(0);
;             s = MFMA(kf[ks & 3], qf[ks], s);
;             if (ks + 4 < 12) kf[ks & 3] = *(const bf16x8*)(kp + (ks + 4) * 16);
;           }
;           __builtin_amdgcn_sched_barrier(0);
;         }
;         bf16x8 vf0[4];
; #pragma unroll
;         for (int dt = 0; dt < 4; ++dt) {
;           const u16* vp = Vs + (dt * 32 + r) * 68 + kh * 32 + 4 * hi;
;           const u32x2 v0 = *(const u32x2*)vp, v1 = *(const u32x2*)(vp + 8);
;           const u32x4 vv = {v0[0], v0[1], v1[0], v1[1]};
;           vf0[dt] = __builtin_bit_cast(bf16x8, vv);
;         }
;         float mx = s[0];
; #pragma unroll
;         for (int i = 1; i < 16; ++i) mx = fmaxf(mx, s[i]);
;         mx = fmaxf(mx, __shfl_xor(mx, 32));
;         const float mn = fmaxf(m, mx);
;         const float alpha = __builtin_amdgcn_exp2f(m - mn);
;         const bool resc = __builtin_amdgcn_ballot_w64(mn > m) != 0ull;
;         m = mn;
;         float rsum = 0.f;
; #pragma unroll
;         for (int i = 0; i < 16; ++i) { s[i] = __builtin_amdgcn_exp2f(s[i] - mn); rsum += s[i]; }
;         l = l * alpha + rsum;
;         if (resc) {
; #pragma unroll
;           for (int dt = 0; dt < 4; ++dt)
; #pragma unroll
;             for (int i = 0; i < 16; ++i) O[dt][i] *= alpha;
;         }
.LBB0_642:
	ds_read_b128 v[68:71], v225 offset:16
	ds_read_b128 v[172:175], v225 offset:48
	ds_read_b128 v[176:179], v225 offset:80
	ds_read_b128 v[180:183], v225 offset:112
	s_waitcnt lgkmcnt(3)
	s_setprio 1
	v_mfma_f32_32x32x16_bf16 v[68:83], v[68:71], v[84:87], 0
	ds_read_b128 v[184:187], v225 offset:144
	s_waitcnt lgkmcnt(3)
	v_mfma_f32_32x32x16_bf16 v[68:83], v[172:175], v[88:91], v[68:83]
	ds_read_b128 v[232:235], v225 offset:176
	s_waitcnt lgkmcnt(3)
	v_mfma_f32_32x32x16_bf16 v[68:83], v[176:179], v[92:95], v[68:83]
	ds_read_b128 v[172:175], v225 offset:208
	s_waitcnt lgkmcnt(3)
	v_mfma_f32_32x32x16_bf16 v[68:83], v[180:183], v[96:99], v[68:83]
	ds_read_b128 v[176:179], v225 offset:240
	s_waitcnt lgkmcnt(3)
	v_mfma_f32_32x32x16_bf16 v[68:83], v[184:187], v[100:103], v[68:83]
	ds_read_b128 v[180:183], v225 offset:272
	s_waitcnt lgkmcnt(3)
	v_mfma_f32_32x32x16_bf16 v[68:83], v[232:235], v[104:107], v[68:83]
	ds_read_b128 v[184:187], v225 offset:304
	s_waitcnt lgkmcnt(3)
	v_mfma_f32_32x32x16_bf16 v[68:83], v[172:175], v[108:111], v[68:83]
	ds_read_b128 v[232:235], v225 offset:336
	s_waitcnt lgkmcnt(3)
	v_mfma_f32_32x32x16_bf16 v[68:83], v[176:179], v[112:115], v[68:83]
	ds_read_b128 v[172:175], v225 offset:368
	s_waitcnt lgkmcnt(3)
	v_mfma_f32_32x32x16_bf16 v[68:83], v[180:183], v[116:119], v[68:83]
	s_waitcnt lgkmcnt(2)
	v_mfma_f32_32x32x16_bf16 v[68:83], v[184:187], v[120:123], v[68:83]
	s_waitcnt lgkmcnt(1)
	v_mfma_f32_32x32x16_bf16 v[68:83], v[232:235], v[124:127], v[68:83]
	s_waitcnt lgkmcnt(0)
	v_mfma_f32_32x32x16_bf16 v[68:83], v[172:175], v[128:131], v[68:83]
	s_setprio 0
	v_add_u32_e32 v3, 0x6000, v226
	ds_read2_b64 v[172:175], v3 offset0:130 offset1:132
	v_add_u32_e32 v3, 0x7000, v226
	ds_read2_b64 v[176:179], v3 offset0:162 offset1:164
	s_nop 7
	v_max_f32_e32 v3, v69, v69
	v_max_f32_e32 v180, v68, v68
	v_max_f32_e32 v3, v180, v3
	v_max3_f32 v3, v3, v70, v71
	v_max3_f32 v3, v3, v72, v73
	v_max3_f32 v3, v3, v74, v75
	v_max3_f32 v3, v3, v76, v77
	v_max3_f32 v3, v3, v78, v79
	v_max3_f32 v3, v3, v80, v81
	v_max3_f32 v3, v3, v82, v83
	v_mov_b32_e32 v218, v3
	v_mov_b32_e32 v180, v3
	v_add_u32_e32 v184, 0x8000, v226
	ds_read2_b64 v[184:187], v184 offset0:194 offset1:196
	v_permlane32_swap_b32_e32 v218, v180
	v_max_f32_e32 v218, v218, v180
	v_add_u32_e32 v180, 0x9000, v226
	ds_read2_b64 v[180:183], v180 offset0:226 offset1:228
	s_waitcnt lgkmcnt(2)
	v_max3_f32 v3, v231, v3, v218
	v_sub_f32_e32 v218, v231, v3
	v_exp_f32_e32 v218, v218
	v_cmp_gt_f32_e32 vcc, v3, v231
	s_cbranch_vccz .LBB0_644
	v_pk_mul_f32 v[66:67], v[66:67], v[218:219] op_sel_hi:[1,0]
	v_pk_mul_f32 v[64:65], v[64:65], v[218:219] op_sel_hi:[1,0]
	v_pk_mul_f32 v[62:63], v[62:63], v[218:219] op_sel_hi:[1,0]
	v_pk_mul_f32 v[60:61], v[60:61], v[218:219] op_sel_hi:[1,0]
	v_pk_mul_f32 v[58:59], v[58:59], v[218:219] op_sel_hi:[1,0]
	v_pk_mul_f32 v[56:57], v[56:57], v[218:219] op_sel_hi:[1,0]
	v_pk_mul_f32 v[54:55], v[54:55], v[218:219] op_sel_hi:[1,0]
	v_pk_mul_f32 v[52:53], v[52:53], v[218:219] op_sel_hi:[1,0]
	v_pk_mul_f32 v[50:51], v[50:51], v[218:219] op_sel_hi:[1,0]
	v_pk_mul_f32 v[48:49], v[48:49], v[218:219] op_sel_hi:[1,0]
	v_pk_mul_f32 v[46:47], v[46:47], v[218:219] op_sel_hi:[1,0]
	v_pk_mul_f32 v[44:45], v[44:45], v[218:219] op_sel_hi:[1,0]
	v_pk_mul_f32 v[42:43], v[42:43], v[218:219] op_sel_hi:[1,0]
	v_pk_mul_f32 v[40:41], v[40:41], v[218:219] op_sel_hi:[1,0]
	v_pk_mul_f32 v[38:39], v[38:39], v[218:219] op_sel_hi:[1,0]
	v_pk_mul_f32 v[36:37], v[36:37], v[218:219] op_sel_hi:[1,0]
	v_pk_mul_f32 v[34:35], v[34:35], v[218:219] op_sel_hi:[1,0]
	v_pk_mul_f32 v[32:33], v[32:33], v[218:219] op_sel_hi:[1,0]
	v_pk_mul_f32 v[30:31], v[30:31], v[218:219] op_sel_hi:[1,0]
	v_pk_mul_f32 v[28:29], v[28:29], v[218:219] op_sel_hi:[1,0]
	v_pk_mul_f32 v[26:27], v[26:27], v[218:219] op_sel_hi:[1,0]
	v_pk_mul_f32 v[24:25], v[24:25], v[218:219] op_sel_hi:[1,0]
	v_pk_mul_f32 v[22:23], v[22:23], v[218:219] op_sel_hi:[1,0]
	v_pk_mul_f32 v[20:21], v[20:21], v[218:219] op_sel_hi:[1,0]
	v_pk_mul_f32 v[18:19], v[18:19], v[218:219] op_sel_hi:[1,0]
	v_pk_mul_f32 v[16:17], v[16:17], v[218:219] op_sel_hi:[1,0]
	v_pk_mul_f32 v[14:15], v[14:15], v[218:219] op_sel_hi:[1,0]
	v_pk_mul_f32 v[12:13], v[12:13], v[218:219] op_sel_hi:[1,0]
	v_pk_mul_f32 v[10:11], v[10:11], v[218:219] op_sel_hi:[1,0]
	v_pk_mul_f32 v[8:9], v[8:9], v[218:219] op_sel_hi:[1,0]
	v_pk_mul_f32 v[6:7], v[6:7], v[218:219] op_sel_hi:[1,0]
	v_pk_mul_f32 v[4:5], v[4:5], v[218:219] op_sel_hi:[1,0]
; #define MFMA(a, b, c) __builtin_amdgcn_mfma_f32_32x32x16_bf16((a), (b), (c), 0, 0, 0)
; DI unsigned pk2(float a, float b) { f2_t v = {a, b}; bf2_t r = __builtin_convertvector(v, bf2_t); return __builtin_bit_cast(unsigned, r); }
; DI void phase4(const Params& p, char* smem) {
;     ...
;         float rsum = 0.f;
; #pragma unroll
;         for (int i = 0; i < 16; ++i) { s[i] = __builtin_amdgcn_exp2f(s[i] - mn); rsum += s[i]; }
;         l = l * alpha + rsum;
;         if (resc) {
; #pragma unroll
;           for (int dt = 0; dt < 4; ++dt)
; #pragma unroll
;             for (int i = 0; i < 16; ++i) O[dt][i] *= alpha;
;         }
;         {
;           const u32x4 pu0 = {pk2(s[0], s[1]), pk2(s[2], s[3]), pk2(s[4], s[5]), pk2(s[6], s[7])};
;           const u32x4 pu1 = {pk2(s[8], s[9]), pk2(s[10], s[11]), pk2(s[12], s[13]), pk2(s[14], s[15])};
;           const bf16x8 pf0 = __builtin_bit_cast(bf16x8, pu0), pf1 = __builtin_bit_cast(bf16x8, pu1);
;           bf16x8 vf1[4];
; #pragma unroll
;           for (int dt = 0; dt < 4; ++dt) {
;             const u16* vp = Vs + (dt * 32 + r) * 68 + kh * 32 + 16 + 4 * hi;
;             const u32x2 v0 = *(const u32x2*)vp, v1 = *(const u32x2*)(vp + 8);
;             const u32x4 vv = {v0[0], v0[1], v1[0], v1[1]};
;             vf1[dt] = __builtin_bit_cast(bf16x8, vv);
;           }
;           __builtin_amdgcn_sched_barrier(0);
; #pragma unroll
;           for (int dt = 0; dt < 4; ++dt) O[dt] = MFMA(vf0[dt], pf0, O[dt]);
; #pragma unroll
;           for (int dt = 0; dt < 4; ++dt) O[dt] = MFMA(vf1[dt], pf1, O[dt]);
;         }
;       }
.LBB0_644:
	v_sub_f32_e32 v68, v68, v3
	v_exp_f32_e32 v231, v68
	v_sub_f32_e32 v68, v69, v3
	v_exp_f32_e32 v69, v68
	v_sub_f32_e32 v68, v70, v3
	v_sub_f32_e32 v70, v72, v3
	v_exp_f32_e32 v232, v68
	v_sub_f32_e32 v68, v71, v3
	v_exp_f32_e32 v72, v70
	v_sub_f32_e32 v70, v73, v3
	v_exp_f32_e32 v71, v68
	v_exp_f32_e32 v73, v70
	v_sub_f32_e32 v70, v74, v3
	v_add_f32_e32 v68, 0, v231
	v_exp_f32_e32 v74, v70
	v_sub_f32_e32 v70, v75, v3
	v_add_f32_e32 v68, v69, v68
	v_exp_f32_e32 v75, v70
	v_sub_f32_e32 v70, v76, v3
	v_add_f32_e32 v68, v232, v68
	v_exp_f32_e32 v240, v70
	v_sub_f32_e32 v70, v77, v3
	v_add_f32_e32 v68, v71, v68
	v_exp_f32_e32 v241, v70
	v_sub_f32_e32 v70, v78, v3
	v_add_f32_e32 v68, v72, v68
	v_exp_f32_e32 v242, v70
	v_sub_f32_e32 v70, v79, v3
	v_add_f32_e32 v68, v73, v68
	v_exp_f32_e32 v243, v70
	v_sub_f32_e32 v70, v80, v3
	v_add_f32_e32 v68, v74, v68
	v_exp_f32_e32 v244, v70
	v_sub_f32_e32 v70, v81, v3
	v_add_f32_e32 v68, v75, v68
	v_exp_f32_e32 v245, v70
	v_sub_f32_e32 v70, v82, v3
	v_add_f32_e32 v68, v240, v68
	v_exp_f32_e32 v82, v70
	v_sub_f32_e32 v70, v83, v3
	v_add_f32_e32 v68, v241, v68
	v_exp_f32_e32 v83, v70
	v_cvt_pk_bf16_f32 v70, v231, v69
	v_add_u32_e32 v69, 0x6000, v227
	v_add_f32_e32 v68, v242, v68
	v_cvt_pk_bf16_f32 v72, v72, v73
	v_cvt_pk_bf16_f32 v73, v74, v75
	ds_read2_b64 v[74:77], v69 offset0:134 offset1:136
	v_add_u32_e32 v69, 0x7000, v227
	v_add_f32_e32 v68, v243, v68
	ds_read2_b64 v[78:81], v69 offset0:166 offset1:168
	v_add_u32_e32 v69, 0x8000, v227
	v_add_f32_e32 v68, v244, v68
	v_cvt_pk_bf16_f32 v71, v232, v71
	ds_read2_b64 v[232:235], v69 offset0:198 offset1:200
	v_add_u32_e32 v69, 0x9000, v227
	v_add_f32_e32 v68, v245, v68
	ds_read2_b64 v[236:239], v69 offset0:230 offset1:232
	v_add_f32_e32 v68, v82, v68
	v_add_f32_e32 v68, v83, v68
	v_fmac_f32_e32 v68, v201, v218
	v_cvt_pk_bf16_f32 v240, v240, v241
	v_cvt_pk_bf16_f32 v241, v242, v243
	v_cvt_pk_bf16_f32 v242, v244, v245
	v_cvt_pk_bf16_f32 v243, v82, v83
	s_setprio 1
	v_mfma_f32_32x32x16_bf16 v[52:67], v[172:175], v[70:73], v[52:67]
	s_add_i32 s22, s22, 1
	s_cmp_eq_u32 s7, s22
	v_mfma_f32_32x32x16_bf16 v[36:51], v[176:179], v[70:73], v[36:51]
	s_waitcnt lgkmcnt(5)
	v_mfma_f32_32x32x16_bf16 v[20:35], v[184:187], v[70:73], v[20:35]
	s_waitcnt lgkmcnt(4)
	v_mfma_f32_32x32x16_bf16 v[4:19], v[180:183], v[70:73], v[4:19]
	s_waitcnt lgkmcnt(3)
	v_mfma_f32_32x32x16_bf16 v[52:67], v[74:77], v[240:243], v[52:67]
	s_waitcnt lgkmcnt(2)
	v_mfma_f32_32x32x16_bf16 v[36:51], v[78:81], v[240:243], v[36:51]
	s_waitcnt lgkmcnt(1)
	v_mfma_f32_32x32x16_bf16 v[20:35], v[232:235], v[240:243], v[20:35]
	s_waitcnt lgkmcnt(0)
	v_mfma_f32_32x32x16_bf16 v[4:19], v[236:239], v[240:243], v[4:19]
	s_setprio 0
	s_cbranch_scc1 .LBB0_646
	v_mov_b32_e32 v201, v68
	v_mov_b32_e32 v231, v3
	s_branch .LBB0_640
